# MLA block epilogue: packed pairs transposed through per-wave LDS scratch, 8 dwordx4 stores per wave instead of 64 dword stores
# baseline (speedup 1.0000x reference)
; __device__ __forceinline__ int crow(int r, int hi) { return (r & 3) + 8 * (r >> 2) + 4 * hi; }
; __device__ __forceinline__ void mla_block(const MlaRef& cur, char* lds) {
;     ...
;     if (hi == 0) li_l[r32] = l_reg; asm volatile("s_waitcnt lgkmcnt(0)" ::: "memory");
;     float rli[16];
; #pragma unroll
;     for (int r = 0; r < 16; ++r) rli[r] = __builtin_amdgcn_rcpf(li_l[crow(r, hi)]);
;     bf16* Ow = cur.O + (size_t)(wid * QBLK) * MLA_OS;
; #pragma unroll
;     for (int r = 0; r < 16; ++r) { const int orow = crow(r, hi);
; #pragma unroll
;         for (int d0 = 0; d0 < 4; ++d0) { const float v = o[d0][r] * rli[r];
;             const float vn = __shfl_xor(v, 1);
;             if ((r32 & 1) == 0) *(unsigned*)(Ow + (size_t)orow * MLA_OS + d0 * 32 + r32) = cvtpk(v, vn); } }
.LBB0_850:
	s_and_saveexec_b64 s[6:7], s[4:5]
	ds_write_b32 v187, v196
	s_or_b64 exec, exec, s[6:7]
	s_waitcnt lgkmcnt(0)
	ds_read_b128 v[78:81], v183
	ds_read_b128 v[74:77], v183 offset:32
	ds_read_b128 v[70:73], v183 offset:64
	ds_read_b128 v[66:69], v183 offset:96
	s_or_b32 s4, s25, s47
	s_ashr_i32 s5, s4, 31
	s_lshl_b64 s[4:5], s[4:5], 11
	s_add_u32 s4, s26, s4
	s_addc_u32 s5, s27, s5
	s_add_u32 s6, s4, s48
	s_addc_u32 s7, s5, 0
	s_ashr_i32 s25, s24, 31
	s_lshl_b64 s[4:5], s[24:25], 11
	s_add_u32 s6, s6, s4
	s_addc_u32 s7, s7, s5
	s_add_u32 s28, s6, s12
	s_addc_u32 s29, s7, s13
	v_lshrrev_b32_e32 v92, 6, v178
	v_mul_u32_u24_e32 v92, 0x1600, v92
	v_add_u32_e32 v92, 0x15000, v92
	v_mul_u32_u24_e32 v82, 576, v176
	v_lshl_add_u32 v82, v177, 1, v82
	v_add_u32_e32 v82, v82, v92
	v_bfe_u32 v83, v175, 3, 3
	v_and_b32_e32 v88, 7, v175
	v_lshlrev_b32_e32 v88, 4, v88
	v_lshl_add_u32 v89, v83, 11, v88
	v_mul_u32_u24_e32 v83, 144, v83
	v_add3_u32 v83, v83, v88, v92
	v_mov_b32_e32 v88, v89
	v_add_u32_e32 v89, 0x4000, v88
	v_add_u32_e32 v90, 0x8000, v88
	v_add_u32_e32 v91, 0xc000, v88
	v_and_b32_e32 v0, 1, v175
	v_cmp_eq_u32_e64 s[4:5], 0, v0
	s_waitcnt lgkmcnt(0)
	v_rcp_f32_e32 v78, v78
	v_rcp_f32_e32 v79, v79
	v_rcp_f32_e32 v80, v80
	v_rcp_f32_e32 v81, v81
	v_rcp_f32_e32 v74, v74
	v_rcp_f32_e32 v75, v75
	v_rcp_f32_e32 v76, v76
	v_rcp_f32_e32 v77, v77
	v_rcp_f32_e32 v70, v70
	v_rcp_f32_e32 v71, v71
	v_rcp_f32_e32 v72, v72
	v_rcp_f32_e32 v73, v73
	v_rcp_f32_e32 v66, v66
	v_rcp_f32_e32 v67, v67
	v_rcp_f32_e32 v68, v68
	v_rcp_f32_e32 v69, v69
	v_mul_f32_e32 v50, v50, v78
	v_mul_f32_e32 v34, v34, v78
	v_mul_f32_e32 v18, v18, v78
	v_mul_f32_e32 v2, v2, v78
	v_mul_f32_e32 v51, v51, v79
	v_mul_f32_e32 v35, v35, v79
	v_mul_f32_e32 v19, v19, v79
	v_mul_f32_e32 v3, v3, v79
	v_mul_f32_e32 v52, v52, v80
	v_mul_f32_e32 v36, v36, v80
	v_mul_f32_e32 v20, v20, v80
	v_mul_f32_e32 v4, v4, v80
	v_mul_f32_e32 v53, v53, v81
	v_mul_f32_e32 v37, v37, v81
	v_mul_f32_e32 v21, v21, v81
	v_mul_f32_e32 v5, v5, v81
	v_mul_f32_e32 v54, v54, v74
	v_mul_f32_e32 v38, v38, v74
	v_mul_f32_e32 v22, v22, v74
	v_mul_f32_e32 v6, v6, v74
	v_mul_f32_e32 v55, v55, v75
	v_mul_f32_e32 v39, v39, v75
	v_mul_f32_e32 v23, v23, v75
	v_mul_f32_e32 v7, v7, v75
	v_mul_f32_e32 v56, v56, v76
	v_mul_f32_e32 v40, v40, v76
	v_mul_f32_e32 v24, v24, v76
	v_mul_f32_e32 v8, v8, v76
	v_mul_f32_e32 v57, v57, v77
	v_mul_f32_e32 v41, v41, v77
	v_mul_f32_e32 v25, v25, v77
	v_mul_f32_e32 v9, v9, v77
	v_mul_f32_e32 v58, v58, v70
	v_mul_f32_e32 v42, v42, v70
	v_mul_f32_e32 v26, v26, v70
	v_mul_f32_e32 v10, v10, v70
	v_mul_f32_e32 v59, v59, v71
	v_mul_f32_e32 v43, v43, v71
	v_mul_f32_e32 v27, v27, v71
	v_mul_f32_e32 v11, v11, v71
	v_mul_f32_e32 v60, v60, v72
	v_mul_f32_e32 v44, v44, v72
	v_mul_f32_e32 v28, v28, v72
	v_mul_f32_e32 v12, v12, v72
	v_mul_f32_e32 v61, v61, v73
	v_mul_f32_e32 v45, v45, v73
	v_mul_f32_e32 v29, v29, v73
	v_mul_f32_e32 v13, v13, v73
	v_mul_f32_e32 v62, v62, v66
	v_mul_f32_e32 v46, v46, v66
	v_mul_f32_e32 v30, v30, v66
	v_mul_f32_e32 v14, v14, v66
	v_mul_f32_e32 v63, v63, v67
	v_mul_f32_e32 v47, v47, v67
	v_mul_f32_e32 v31, v31, v67
	v_mul_f32_e32 v15, v15, v67
	v_mul_f32_e32 v64, v64, v68
	v_mul_f32_e32 v48, v48, v68
	v_mul_f32_e32 v32, v32, v68
	v_mul_f32_e32 v16, v16, v68
	v_mul_f32_e32 v65, v65, v69
	v_mul_f32_e32 v49, v49, v69
	v_mul_f32_e32 v33, v33, v69
	v_mul_f32_e32 v17, v17, v69
	v_mov_b32_dpp v84, v50 quad_perm:[1,0,3,2] row_mask:0xf bank_mask:0xf
	v_cvt_pk_bf16_f32 v50, v50, v84
	v_mov_b32_dpp v85, v34 quad_perm:[1,0,3,2] row_mask:0xf bank_mask:0xf
	v_cvt_pk_bf16_f32 v34, v34, v85
	v_mov_b32_dpp v86, v18 quad_perm:[1,0,3,2] row_mask:0xf bank_mask:0xf
	v_cvt_pk_bf16_f32 v18, v18, v86
	v_mov_b32_dpp v87, v2 quad_perm:[1,0,3,2] row_mask:0xf bank_mask:0xf
	v_cvt_pk_bf16_f32 v2, v2, v87
	v_mov_b32_dpp v84, v51 quad_perm:[1,0,3,2] row_mask:0xf bank_mask:0xf
	v_cvt_pk_bf16_f32 v51, v51, v84
	v_mov_b32_dpp v85, v35 quad_perm:[1,0,3,2] row_mask:0xf bank_mask:0xf
	v_cvt_pk_bf16_f32 v35, v35, v85
	v_mov_b32_dpp v86, v19 quad_perm:[1,0,3,2] row_mask:0xf bank_mask:0xf
	v_cvt_pk_bf16_f32 v19, v19, v86
	v_mov_b32_dpp v87, v3 quad_perm:[1,0,3,2] row_mask:0xf bank_mask:0xf
	v_cvt_pk_bf16_f32 v3, v3, v87
	v_mov_b32_dpp v84, v52 quad_perm:[1,0,3,2] row_mask:0xf bank_mask:0xf
	v_cvt_pk_bf16_f32 v52, v52, v84
	v_mov_b32_dpp v85, v36 quad_perm:[1,0,3,2] row_mask:0xf bank_mask:0xf
	v_cvt_pk_bf16_f32 v36, v36, v85
	v_mov_b32_dpp v86, v20 quad_perm:[1,0,3,2] row_mask:0xf bank_mask:0xf
	v_cvt_pk_bf16_f32 v20, v20, v86
	v_mov_b32_dpp v87, v4 quad_perm:[1,0,3,2] row_mask:0xf bank_mask:0xf
	v_cvt_pk_bf16_f32 v4, v4, v87
	v_mov_b32_dpp v84, v53 quad_perm:[1,0,3,2] row_mask:0xf bank_mask:0xf
	v_cvt_pk_bf16_f32 v53, v53, v84
	v_mov_b32_dpp v85, v37 quad_perm:[1,0,3,2] row_mask:0xf bank_mask:0xf
	v_cvt_pk_bf16_f32 v37, v37, v85
	v_mov_b32_dpp v86, v21 quad_perm:[1,0,3,2] row_mask:0xf bank_mask:0xf
	v_cvt_pk_bf16_f32 v21, v21, v86
	v_mov_b32_dpp v87, v5 quad_perm:[1,0,3,2] row_mask:0xf bank_mask:0xf
	v_cvt_pk_bf16_f32 v5, v5, v87
	v_mov_b32_dpp v84, v54 quad_perm:[1,0,3,2] row_mask:0xf bank_mask:0xf
	v_cvt_pk_bf16_f32 v54, v54, v84
	v_mov_b32_dpp v85, v38 quad_perm:[1,0,3,2] row_mask:0xf bank_mask:0xf
	v_cvt_pk_bf16_f32 v38, v38, v85
	v_mov_b32_dpp v86, v22 quad_perm:[1,0,3,2] row_mask:0xf bank_mask:0xf
	v_cvt_pk_bf16_f32 v22, v22, v86
	v_mov_b32_dpp v87, v6 quad_perm:[1,0,3,2] row_mask:0xf bank_mask:0xf
	v_cvt_pk_bf16_f32 v6, v6, v87
	v_mov_b32_dpp v84, v55 quad_perm:[1,0,3,2] row_mask:0xf bank_mask:0xf
	v_cvt_pk_bf16_f32 v55, v55, v84
	v_mov_b32_dpp v85, v39 quad_perm:[1,0,3,2] row_mask:0xf bank_mask:0xf
; __device__ __forceinline__ int crow(int r, int hi) { return (r & 3) + 8 * (r >> 2) + 4 * hi; }
; __device__ __forceinline__ void mla_block(const MlaRef& cur, char* lds) {
;     ...
;     for (int r = 0; r < 16; ++r) { const int orow = crow(r, hi);
; #pragma unroll
;         for (int d0 = 0; d0 < 4; ++d0) { const float v = o[d0][r] * rli[r];
;             const float vn = __shfl_xor(v, 1);
;             if ((r32 & 1) == 0) *(unsigned*)(Ow + (size_t)orow * MLA_OS + d0 * 32 + r32) = cvtpk(v, vn); } }
	v_cvt_pk_bf16_f32 v39, v39, v85
	v_mov_b32_dpp v86, v23 quad_perm:[1,0,3,2] row_mask:0xf bank_mask:0xf
	v_cvt_pk_bf16_f32 v23, v23, v86
	v_mov_b32_dpp v87, v7 quad_perm:[1,0,3,2] row_mask:0xf bank_mask:0xf
	v_cvt_pk_bf16_f32 v7, v7, v87
	v_mov_b32_dpp v84, v56 quad_perm:[1,0,3,2] row_mask:0xf bank_mask:0xf
	v_cvt_pk_bf16_f32 v56, v56, v84
	v_mov_b32_dpp v85, v40 quad_perm:[1,0,3,2] row_mask:0xf bank_mask:0xf
	v_cvt_pk_bf16_f32 v40, v40, v85
	v_mov_b32_dpp v86, v24 quad_perm:[1,0,3,2] row_mask:0xf bank_mask:0xf
	v_cvt_pk_bf16_f32 v24, v24, v86
	v_mov_b32_dpp v87, v8 quad_perm:[1,0,3,2] row_mask:0xf bank_mask:0xf
	v_cvt_pk_bf16_f32 v8, v8, v87
	v_mov_b32_dpp v84, v57 quad_perm:[1,0,3,2] row_mask:0xf bank_mask:0xf
	v_cvt_pk_bf16_f32 v57, v57, v84
	v_mov_b32_dpp v85, v41 quad_perm:[1,0,3,2] row_mask:0xf bank_mask:0xf
	v_cvt_pk_bf16_f32 v41, v41, v85
	v_mov_b32_dpp v86, v25 quad_perm:[1,0,3,2] row_mask:0xf bank_mask:0xf
	v_cvt_pk_bf16_f32 v25, v25, v86
	v_mov_b32_dpp v87, v9 quad_perm:[1,0,3,2] row_mask:0xf bank_mask:0xf
	v_cvt_pk_bf16_f32 v9, v9, v87
	v_mov_b32_dpp v84, v58 quad_perm:[1,0,3,2] row_mask:0xf bank_mask:0xf
	v_cvt_pk_bf16_f32 v58, v58, v84
	v_mov_b32_dpp v85, v42 quad_perm:[1,0,3,2] row_mask:0xf bank_mask:0xf
	v_cvt_pk_bf16_f32 v42, v42, v85
	v_mov_b32_dpp v86, v26 quad_perm:[1,0,3,2] row_mask:0xf bank_mask:0xf
	v_cvt_pk_bf16_f32 v26, v26, v86
	v_mov_b32_dpp v87, v10 quad_perm:[1,0,3,2] row_mask:0xf bank_mask:0xf
	v_cvt_pk_bf16_f32 v10, v10, v87
	v_mov_b32_dpp v84, v59 quad_perm:[1,0,3,2] row_mask:0xf bank_mask:0xf
	v_cvt_pk_bf16_f32 v59, v59, v84
	v_mov_b32_dpp v85, v43 quad_perm:[1,0,3,2] row_mask:0xf bank_mask:0xf
	v_cvt_pk_bf16_f32 v43, v43, v85
	v_mov_b32_dpp v86, v27 quad_perm:[1,0,3,2] row_mask:0xf bank_mask:0xf
	v_cvt_pk_bf16_f32 v27, v27, v86
	v_mov_b32_dpp v87, v11 quad_perm:[1,0,3,2] row_mask:0xf bank_mask:0xf
	v_cvt_pk_bf16_f32 v11, v11, v87
	v_mov_b32_dpp v84, v60 quad_perm:[1,0,3,2] row_mask:0xf bank_mask:0xf
	v_cvt_pk_bf16_f32 v60, v60, v84
	v_mov_b32_dpp v85, v44 quad_perm:[1,0,3,2] row_mask:0xf bank_mask:0xf
	v_cvt_pk_bf16_f32 v44, v44, v85
	v_mov_b32_dpp v86, v28 quad_perm:[1,0,3,2] row_mask:0xf bank_mask:0xf
	v_cvt_pk_bf16_f32 v28, v28, v86
	v_mov_b32_dpp v87, v12 quad_perm:[1,0,3,2] row_mask:0xf bank_mask:0xf
	v_cvt_pk_bf16_f32 v12, v12, v87
	v_mov_b32_dpp v84, v61 quad_perm:[1,0,3,2] row_mask:0xf bank_mask:0xf
	v_cvt_pk_bf16_f32 v61, v61, v84
	v_mov_b32_dpp v85, v45 quad_perm:[1,0,3,2] row_mask:0xf bank_mask:0xf
	v_cvt_pk_bf16_f32 v45, v45, v85
	v_mov_b32_dpp v86, v29 quad_perm:[1,0,3,2] row_mask:0xf bank_mask:0xf
	v_cvt_pk_bf16_f32 v29, v29, v86
	v_mov_b32_dpp v87, v13 quad_perm:[1,0,3,2] row_mask:0xf bank_mask:0xf
	v_cvt_pk_bf16_f32 v13, v13, v87
	v_mov_b32_dpp v84, v62 quad_perm:[1,0,3,2] row_mask:0xf bank_mask:0xf
	v_cvt_pk_bf16_f32 v62, v62, v84
	v_mov_b32_dpp v85, v46 quad_perm:[1,0,3,2] row_mask:0xf bank_mask:0xf
	v_cvt_pk_bf16_f32 v46, v46, v85
	v_mov_b32_dpp v86, v30 quad_perm:[1,0,3,2] row_mask:0xf bank_mask:0xf
	v_cvt_pk_bf16_f32 v30, v30, v86
	v_mov_b32_dpp v87, v14 quad_perm:[1,0,3,2] row_mask:0xf bank_mask:0xf
	v_cvt_pk_bf16_f32 v14, v14, v87
	v_mov_b32_dpp v84, v63 quad_perm:[1,0,3,2] row_mask:0xf bank_mask:0xf
	v_cvt_pk_bf16_f32 v63, v63, v84
	v_mov_b32_dpp v85, v47 quad_perm:[1,0,3,2] row_mask:0xf bank_mask:0xf
	v_cvt_pk_bf16_f32 v47, v47, v85
	v_mov_b32_dpp v86, v31 quad_perm:[1,0,3,2] row_mask:0xf bank_mask:0xf
	v_cvt_pk_bf16_f32 v31, v31, v86
	v_mov_b32_dpp v87, v15 quad_perm:[1,0,3,2] row_mask:0xf bank_mask:0xf
	v_cvt_pk_bf16_f32 v15, v15, v87
	v_mov_b32_dpp v84, v64 quad_perm:[1,0,3,2] row_mask:0xf bank_mask:0xf
	v_cvt_pk_bf16_f32 v64, v64, v84
	v_mov_b32_dpp v85, v48 quad_perm:[1,0,3,2] row_mask:0xf bank_mask:0xf
	v_cvt_pk_bf16_f32 v48, v48, v85
	v_mov_b32_dpp v86, v32 quad_perm:[1,0,3,2] row_mask:0xf bank_mask:0xf
	v_cvt_pk_bf16_f32 v32, v32, v86
	v_mov_b32_dpp v87, v16 quad_perm:[1,0,3,2] row_mask:0xf bank_mask:0xf
	v_cvt_pk_bf16_f32 v16, v16, v87
	v_mov_b32_dpp v84, v65 quad_perm:[1,0,3,2] row_mask:0xf bank_mask:0xf
	v_cvt_pk_bf16_f32 v65, v65, v84
	v_mov_b32_dpp v85, v49 quad_perm:[1,0,3,2] row_mask:0xf bank_mask:0xf
	v_cvt_pk_bf16_f32 v49, v49, v85
	v_mov_b32_dpp v86, v33 quad_perm:[1,0,3,2] row_mask:0xf bank_mask:0xf
	v_cvt_pk_bf16_f32 v33, v33, v86
	v_mov_b32_dpp v87, v17 quad_perm:[1,0,3,2] row_mask:0xf bank_mask:0xf
	v_cvt_pk_bf16_f32 v17, v17, v87
	s_mov_b64 s[6:7], exec
	s_mov_b64 exec, s[4:5]
	ds_write_b32 v82, v50
	ds_write_b32 v82, v34 offset:64
	ds_write_b32 v82, v51 offset:144
	ds_write_b32 v82, v35 offset:208
	ds_write_b32 v82, v52 offset:288
	ds_write_b32 v82, v36 offset:352
	ds_write_b32 v82, v53 offset:432
	ds_write_b32 v82, v37 offset:496
	ds_write_b32 v82, v54 offset:1152
	ds_write_b32 v82, v38 offset:1216
	ds_write_b32 v82, v55 offset:1296
	ds_write_b32 v82, v39 offset:1360
	ds_write_b32 v82, v56 offset:1440
	ds_write_b32 v82, v40 offset:1504
	ds_write_b32 v82, v57 offset:1584
	ds_write_b32 v82, v41 offset:1648
	ds_write_b32 v82, v58 offset:2304
	ds_write_b32 v82, v42 offset:2368
	ds_write_b32 v82, v59 offset:2448
	ds_write_b32 v82, v43 offset:2512
	ds_write_b32 v82, v60 offset:2592
	ds_write_b32 v82, v44 offset:2656
	ds_write_b32 v82, v61 offset:2736
	ds_write_b32 v82, v45 offset:2800
	ds_write_b32 v82, v62 offset:3456
	ds_write_b32 v82, v46 offset:3520
	ds_write_b32 v82, v63 offset:3600
	ds_write_b32 v82, v47 offset:3664
	ds_write_b32 v82, v64 offset:3744
	ds_write_b32 v82, v48 offset:3808
	ds_write_b32 v82, v65 offset:3888
	ds_write_b32 v82, v49 offset:3952
	s_mov_b64 exec, s[6:7]
	s_waitcnt lgkmcnt(0)
; __device__ __forceinline__ int crow(int r, int hi) { return (r & 3) + 8 * (r >> 2) + 4 * hi; }
; __device__ __forceinline__ void mla_block(const MlaRef& cur, char* lds) {
;     ...
;     bf16* Ow = cur.O + (size_t)(wid * QBLK) * MLA_OS;
; #pragma unroll
;     for (int r = 0; r < 16; ++r) { const int orow = crow(r, hi);
; #pragma unroll
;         for (int d0 = 0; d0 < 4; ++d0) { const float v = o[d0][r] * rli[r];
;             const float vn = __shfl_xor(v, 1);
;             if ((r32 & 1) == 0) *(unsigned*)(Ow + (size_t)orow * MLA_OS + d0 * 32 + r32) = cvtpk(v, vn); } }
	ds_read_b128 v[66:69], v83
	ds_read_b128 v[70:73], v83 offset:1152
	ds_read_b128 v[74:77], v83 offset:2304
	ds_read_b128 v[78:81], v83 offset:3456
	s_waitcnt lgkmcnt(3)
	global_store_dwordx4 v88, v[66:69], s[28:29]
	s_waitcnt lgkmcnt(2)
	global_store_dwordx4 v89, v[70:73], s[28:29]
	s_waitcnt lgkmcnt(1)
	global_store_dwordx4 v90, v[74:77], s[28:29]
	s_waitcnt lgkmcnt(0)
	global_store_dwordx4 v91, v[78:81], s[28:29]
	s_mov_b64 exec, s[4:5]
	ds_write_b32 v82, v18
	ds_write_b32 v82, v2 offset:64
	ds_write_b32 v82, v19 offset:144
	ds_write_b32 v82, v3 offset:208
	ds_write_b32 v82, v20 offset:288
	ds_write_b32 v82, v4 offset:352
	ds_write_b32 v82, v21 offset:432
	ds_write_b32 v82, v5 offset:496
	ds_write_b32 v82, v22 offset:1152
	ds_write_b32 v82, v6 offset:1216
	ds_write_b32 v82, v23 offset:1296
	ds_write_b32 v82, v7 offset:1360
	ds_write_b32 v82, v24 offset:1440
	ds_write_b32 v82, v8 offset:1504
	ds_write_b32 v82, v25 offset:1584
	ds_write_b32 v82, v9 offset:1648
	ds_write_b32 v82, v26 offset:2304
	ds_write_b32 v82, v10 offset:2368
	ds_write_b32 v82, v27 offset:2448
	ds_write_b32 v82, v11 offset:2512
	ds_write_b32 v82, v28 offset:2592
	ds_write_b32 v82, v12 offset:2656
	ds_write_b32 v82, v29 offset:2736
	ds_write_b32 v82, v13 offset:2800
	ds_write_b32 v82, v30 offset:3456
	ds_write_b32 v82, v14 offset:3520
	ds_write_b32 v82, v31 offset:3600
	ds_write_b32 v82, v15 offset:3664
	ds_write_b32 v82, v32 offset:3744
	ds_write_b32 v82, v16 offset:3808
	ds_write_b32 v82, v33 offset:3888
	ds_write_b32 v82, v17 offset:3952
	s_mov_b64 exec, s[6:7]
	s_waitcnt lgkmcnt(0)
	ds_read_b128 v[66:69], v83
	ds_read_b128 v[70:73], v83 offset:1152
	ds_read_b128 v[74:77], v83 offset:2304
	ds_read_b128 v[78:81], v83 offset:3456
	s_waitcnt lgkmcnt(3)
	global_store_dwordx4 v88, v[66:69], s[28:29] offset:128
	s_waitcnt lgkmcnt(2)
	global_store_dwordx4 v89, v[70:73], s[28:29] offset:128
	s_waitcnt lgkmcnt(1)
	global_store_dwordx4 v90, v[74:77], s[28:29] offset:128
	s_waitcnt lgkmcnt(0)
	global_store_dwordx4 v91, v[78:81], s[28:29] offset:128
	s_and_saveexec_b64 s[6:7], s[4:5]
	s_branch .LBB0_835
